# adds E22 (FoX next-unit tile-skip search runs downward from the current value) and E23 (band attention step B reads next K fragments unconditionally: 4 branches removed from the P.V MFMA stream), stac
# baseline (speedup 1.0000x reference)
.LBB0_665:
	s_waitcnt lgkmcnt(14)
	v_mfma_f32_32x32x16_bf16 v[0:15], v[116:119], v[168:171], v[0:15]
	v_exp_f32_e32 v48, v48
	v_exp_f32_e32 v49, v49
	v_exp_f32_e32 v50, v50
	v_exp_f32_e32 v51, v51
	s_waitcnt lgkmcnt(12)
	v_mfma_f32_32x32x16_bf16 v[16:31], v[116:119], v[164:167], v[16:31]
	v_exp_f32_e32 v52, v52
	v_exp_f32_e32 v53, v53
	v_exp_f32_e32 v54, v54
	v_exp_f32_e32 v55, v55
	v_add_u32_e32 v73, s79, v177
	ds_read_b128 v[156:159], v73
	ds_read_b128 v[148:151], v73 offset:512
.LBB0_667:
	s_waitcnt lgkmcnt(10)
	v_mfma_f32_32x32x16_bf16 v[0:15], v[108:111], v[160:163], v[0:15]
	v_exp_f32_e32 v56, v56
	v_exp_f32_e32 v57, v57
	v_exp_f32_e32 v58, v58
	v_exp_f32_e32 v59, v59
	ds_read_b128 v[152:155], v73 offset:2048
	ds_read_b128 v[144:147], v73 offset:2560
.LBB0_669:
	s_waitcnt lgkmcnt(8)
	v_mfma_f32_32x32x16_bf16 v[16:31], v[108:111], v[88:91], v[16:31]
	v_exp_f32_e32 v60, v60
	v_exp_f32_e32 v61, v61
	v_exp_f32_e32 v62, v62
	v_exp_f32_e32 v63, v63
	ds_read_b128 v[140:143], v73 offset:4096
	ds_read_b128 v[136:139], v73 offset:4608
.LBB0_671:
	s_waitcnt lgkmcnt(6)
	v_mfma_f32_32x32x16_bf16 v[0:15], v[100:103], v[84:87], v[0:15]
	v_exp_f32_e32 v32, v32
	v_exp_f32_e32 v33, v33
	v_exp_f32_e32 v34, v34
	v_exp_f32_e32 v35, v35
	ds_read_b128 v[132:135], v73 offset:6144
	ds_read_b128 v[128:131], v73 offset:6656

.LBB0_859:
	v_add_co_u32_e64 v0, s[2:3], s40, -1
	s_lshl_b32 s8, s40, 2
	v_readfirstlane_b32 s89, v0
	s_andn2_b64 vcc, exec, s[2:3]
	s_mov_b32 s26, 0
	s_cbranch_vccnz .LBB0_864
	s_lshl_b32 s1, s40, 10
	s_add_i32 s1, s1, 0
	s_add_i32 s1, s1, 0x14400
	v_mov_b32_e32 v0, s1
	ds_read_b32 v0, v0
	s_add_i32 s1, s8, -4
	s_mov_b32 s10, 0
	v_readlane_b32 s9, v253, 50
	s_min_i32 s10, s0, s1
	s_max_i32 s10, s10, 0
	s_lshl_b32 s26, s10, 8
	s_add_i32 s9, s9, s26
	s_addk_i32 s9, 0xfe00
.Lts_loop:
	s_mov_b32 s26, s10
	s_cmp_lt_i32 s10, 2
	s_cbranch_scc1 .Lts_zero
	v_mov_b32_e32 v1, s9
	ds_read_b32 v1, v1
	s_add_i32 s10, s10, -2
	s_addk_i32 s9, 0xfe00
	s_waitcnt lgkmcnt(0)
	v_sub_f32_e32 v1, v0, v1
	v_cmp_nlt_f32_e64 s[6:7], v1, -v210
	s_nop 0
	s_and_b64 vcc, exec, s[6:7]
	s_cbranch_vccnz .Lts_loop
	s_branch .LBB0_864
.Lts_zero:
	s_mov_b32 s26, 0
